# nt on the relocated adaLN weight-row loads in phase 6 (streaming, keep the scan's prefetched lines in L2)
# baseline (speedup 1.0000x reference)
; DI float silu(float x) { return x * __builtin_amdgcn_rcpf(1.f + __expf(-x)); }
; DI void p0_phase(const Params& P, LAS unsigned char* lds, int gw, int NGW, int wave, int lane) {
;     ...
;         const float* wp = P.w_ada + ((size_t)l * D + kc * 128) * NMOD + j0;
; #pragma unroll 8
;         for (int k = 0; k < 128; ++k) { const f32x4 w4 = *(const f32x4*)(wp + (size_t)k * NMOD);
;             const float c0 = silu(P.c[kc * 128 + k]), c1 = silu(P.c[D + kc * 128 + k]); a0 += w4 * c0; a1 += w4 * c1; }
.Lada2_842:
	s_mov_b32 s0, 0xfffdc000
	v_add_co_u32_e64 v20, s[0:1], s0, v14
	s_add_u32 s8, s13, s4
	s_nop 0
	v_addc_co_u32_e64 v21, s[0:1], -1, v15, s[0:1]
	s_mov_b32 s0, 0xfffe8000
	s_nop 0
	v_add_co_u32_e64 v24, s[0:1], s0, v14
	v_add_co_u32_e32 v16, vcc, 0xfffd0000, v14
	s_nop 0
	v_addc_co_u32_e64 v25, s[0:1], -1, v15, s[0:1]
	s_mov_b32 s0, 0xffff4000
	s_nop 0
	v_add_co_u32_e64 v28, s[0:1], s0, v14
	s_addc_u32 s9, s14, s5
	s_nop 0
	v_addc_co_u32_e64 v29, s[0:1], -1, v15, s[0:1]
	v_add_co_u32_e64 v32, s[0:1], s31, v14
	global_load_dwordx4 v[8:11], v[14:15], off nt
	s_nop 0
	v_addc_co_u32_e64 v33, s[0:1], 0, v15, s[0:1]
	s_mov_b32 s0, 0x18000
	s_nop 0
	v_add_co_u32_e64 v36, s[0:1], s0, v14
	v_addc_co_u32_e32 v17, vcc, -1, v15, vcc
	s_nop 0
	v_addc_co_u32_e64 v37, s[0:1], 0, v15, s[0:1]
	s_mov_b32 s0, 0x24000
	s_nop 0
	v_add_co_u32_e64 v40, s[0:1], s0, v14
	s_nop 1
	v_addc_co_u32_e64 v41, s[0:1], 0, v15, s[0:1]
	s_mov_b64 s[0:1], 0x60000
	global_load_dwordx4 v[20:23], v[20:21], off nt
	s_nop 0
	global_load_dwordx4 v[24:27], v[24:25], off nt
	s_nop 0
	global_load_dwordx4 v[28:31], v[28:29], off nt
	s_nop 0
	global_load_dwordx4 v[32:35], v[32:33], off nt
	s_nop 0
	global_load_dwordx4 v[36:39], v[36:37], off nt
	s_nop 0
	global_load_dwordx4 v[40:43], v[40:41], off nt
	v_lshl_add_u64 v[14:15], v[14:15], 0, s[0:1]
	global_load_dwordx4 v[44:47], v97, s[8:9]
	global_load_dwordx4 v[48:51], v231, s[8:9]
	global_load_dwordx4 v[52:55], v97, s[8:9] offset:16
	global_load_dwordx4 v[56:59], v[16:17], off nt
	s_add_u32 s0, s8, 0x2000
	s_addc_u32 s1, s9, 0
	global_load_dwordx4 v[60:63], v97, s[0:1] offset:16
	s_add_u32 s4, s4, 32
	s_addc_u32 s5, s5, 0
.Lada2_pair:
	s_mov_b32 s0, 0xfffdc000
	v_add_co_u32_e64 v120, s[0:1], s0, v14
	s_add_u32 s8, s13, s4
	s_nop 0
	v_addc_co_u32_e64 v121, s[0:1], -1, v15, s[0:1]
	s_mov_b32 s0, 0xfffe8000
	s_nop 0
	v_add_co_u32_e64 v124, s[0:1], s0, v14
	v_add_co_u32_e32 v116, vcc, 0xfffd0000, v14
	s_nop 0
	v_addc_co_u32_e64 v125, s[0:1], -1, v15, s[0:1]
	s_mov_b32 s0, 0xffff4000
	s_nop 0
	v_add_co_u32_e64 v128, s[0:1], s0, v14
	s_addc_u32 s9, s14, s5
	s_nop 0
	v_addc_co_u32_e64 v129, s[0:1], -1, v15, s[0:1]
	v_add_co_u32_e64 v132, s[0:1], s31, v14
	global_load_dwordx4 v[108:111], v[14:15], off nt
	s_nop 0
	v_addc_co_u32_e64 v133, s[0:1], 0, v15, s[0:1]
	s_mov_b32 s0, 0x18000
	s_nop 0
	v_add_co_u32_e64 v136, s[0:1], s0, v14
	v_addc_co_u32_e32 v117, vcc, -1, v15, vcc
	s_nop 0
	v_addc_co_u32_e64 v137, s[0:1], 0, v15, s[0:1]
	s_mov_b32 s0, 0x24000
	s_nop 0
	v_add_co_u32_e64 v140, s[0:1], s0, v14
	s_nop 1
	v_addc_co_u32_e64 v141, s[0:1], 0, v15, s[0:1]
	s_mov_b64 s[0:1], 0x60000
	global_load_dwordx4 v[120:123], v[120:121], off nt
	s_nop 0
	global_load_dwordx4 v[124:127], v[124:125], off nt
	s_nop 0
	global_load_dwordx4 v[128:131], v[128:129], off nt
	s_nop 0
	global_load_dwordx4 v[132:135], v[132:133], off nt
	s_nop 0
	global_load_dwordx4 v[136:139], v[136:137], off nt
	s_nop 0
	global_load_dwordx4 v[140:143], v[140:141], off nt
	v_lshl_add_u64 v[14:15], v[14:15], 0, s[0:1]
	global_load_dwordx4 v[144:147], v97, s[8:9]
	global_load_dwordx4 v[148:151], v231, s[8:9]
	global_load_dwordx4 v[152:155], v97, s[8:9] offset:16
	global_load_dwordx4 v[156:159], v[116:117], off nt
	s_add_u32 s0, s8, 0x2000
	s_addc_u32 s1, s9, 0
	global_load_dwordx4 v[160:163], v97, s[0:1] offset:16
	s_add_u32 s4, s4, 32
	s_addc_u32 s5, s5, 0
	s_waitcnt vmcnt(12)
	v_mul_f32_e32 v16, 0xbfb8aa3b, v44
	v_mul_f32_e32 v17, 0xbfb8aa3b, v48
	v_mul_f32_e32 v19, 0xbfb8aa3b, v45
	v_mul_f32_e32 v64, 0xbfb8aa3b, v49
	v_exp_f32_e32 v16, v16
	v_exp_f32_e32 v17, v17
	v_mul_f32_e32 v65, 0xbfb8aa3b, v46
	v_mul_f32_e32 v66, 0xbfb8aa3b, v50
	v_exp_f32_e32 v19, v19
	v_exp_f32_e32 v64, v64
	v_mul_f32_e32 v67, 0xbfb8aa3b, v47
	v_mul_f32_e32 v68, 0xbfb8aa3b, v51
	v_exp_f32_e32 v65, v65
	v_exp_f32_e32 v66, v66
	v_mul_f32_e32 v69, 0xbfb8aa3b, v52
	v_exp_f32_e32 v67, v67
	v_exp_f32_e32 v68, v68
	v_mul_f32_e32 v73, 0xbfb8aa3b, v60
	v_mul_f32_e32 v70, 0xbfb8aa3b, v53
	v_exp_f32_e32 v69, v69
	v_mul_f32_e32 v74, 0xbfb8aa3b, v61
	v_exp_f32_e32 v73, v73
	v_add_f32_e32 v16, 1.0, v16
	v_add_f32_e32 v17, 1.0, v17
	v_mul_f32_e32 v71, 0xbfb8aa3b, v54
	v_exp_f32_e32 v70, v70
	v_mul_f32_e32 v75, 0xbfb8aa3b, v62
	v_exp_f32_e32 v74, v74
	v_add_f32_e32 v19, 1.0, v19
	v_add_f32_e32 v64, 1.0, v64
	v_rcp_f32_e32 v16, v16
	v_rcp_f32_e32 v17, v17
	v_mul_f32_e32 v72, 0xbfb8aa3b, v55
	v_exp_f32_e32 v71, v71
	v_mul_f32_e32 v76, 0xbfb8aa3b, v63
	v_exp_f32_e32 v75, v75
	v_add_f32_e32 v65, 1.0, v65
	v_add_f32_e32 v66, 1.0, v66
	v_rcp_f32_e32 v19, v19
	v_rcp_f32_e32 v64, v64
	v_exp_f32_e32 v72, v72
	v_exp_f32_e32 v76, v76
	v_add_f32_e32 v67, 1.0, v67
	v_add_f32_e32 v68, 1.0, v68
	v_rcp_f32_e32 v65, v65
	v_rcp_f32_e32 v66, v66
	v_add_f32_e32 v69, 1.0, v69
	v_rcp_f32_e32 v67, v67
	v_rcp_f32_e32 v68, v68
	v_add_f32_e32 v73, 1.0, v73
	v_add_f32_e32 v70, 1.0, v70
	v_rcp_f32_e32 v69, v69
	v_add_f32_e32 v74, 1.0, v74
	v_rcp_f32_e32 v73, v73
	v_mul_f32_e32 v16, v44, v16
	v_mul_f32_e32 v44, v48, v17
	v_add_f32_e32 v71, 1.0, v71
	v_rcp_f32_e32 v70, v70
	v_add_f32_e32 v75, 1.0, v75
	v_rcp_f32_e32 v74, v74
	v_mul_f32_e32 v48, v45, v19
	v_mul_f32_e32 v64, v49, v64
	v_pk_fma_f32 v[4:5], v[56:57], v[16:17], v[4:5] op_sel_hi:[1,0,1]
	v_pk_fma_f32 v[6:7], v[58:59], v[16:17], v[6:7] op_sel_hi:[1,0,1]
	v_pk_fma_f32 v[0:1], v[56:57], v[44:45], v[0:1] op_sel_hi:[1,0,1]
	v_pk_fma_f32 v[2:3], v[58:59], v[44:45], v[2:3] op_sel_hi:[1,0,1]
	v_add_f32_e32 v72, 1.0, v72
	v_rcp_f32_e32 v71, v71
	v_add_f32_e32 v76, 1.0, v76
	v_rcp_f32_e32 v75, v75
	v_mul_f32_e32 v46, v46, v65
	v_mul_f32_e32 v50, v50, v66
; DI float silu(float x) { return x * __builtin_amdgcn_rcpf(1.f + __expf(-x)); }
; DI void p0_phase(const Params& P, LAS unsigned char* lds, int gw, int NGW, int wave, int lane) {
;     ...
;         for (int k = 0; k < 128; ++k) { const f32x4 w4 = *(const f32x4*)(wp + (size_t)k * NMOD);
;             const float c0 = silu(P.c[kc * 128 + k]), c1 = silu(P.c[D + kc * 128 + k]); a0 += w4 * c0; a1 += w4 * c1; }
	v_pk_fma_f32 v[6:7], v[22:23], v[48:49], v[6:7] op_sel_hi:[1,0,1]
	v_pk_fma_f32 v[4:5], v[20:21], v[48:49], v[4:5] op_sel_hi:[1,0,1]
	v_pk_fma_f32 v[2:3], v[22:23], v[64:65], v[2:3] op_sel_hi:[1,0,1]
	v_pk_fma_f32 v[0:1], v[20:21], v[64:65], v[0:1] op_sel_hi:[1,0,1]
	v_rcp_f32_e32 v72, v72
	v_rcp_f32_e32 v76, v76
	v_mul_f32_e32 v66, v47, v67
	v_mul_f32_e32 v68, v51, v68
	v_pk_fma_f32 v[6:7], v[26:27], v[46:47], v[6:7] op_sel_hi:[1,0,1]
	v_pk_fma_f32 v[4:5], v[24:25], v[46:47], v[4:5] op_sel_hi:[1,0,1]
	v_pk_fma_f32 v[2:3], v[26:27], v[50:51], v[2:3] op_sel_hi:[1,0,1]
	v_pk_fma_f32 v[0:1], v[24:25], v[50:51], v[0:1] op_sel_hi:[1,0,1]
	v_mul_f32_e32 v52, v52, v69
	v_mul_f32_e32 v16, v60, v73
	v_pk_fma_f32 v[6:7], v[30:31], v[66:67], v[6:7] op_sel_hi:[1,0,1]
	v_pk_fma_f32 v[4:5], v[28:29], v[66:67], v[4:5] op_sel_hi:[1,0,1]
	v_pk_fma_f32 v[2:3], v[30:31], v[68:69], v[2:3] op_sel_hi:[1,0,1]
	v_pk_fma_f32 v[0:1], v[28:29], v[68:69], v[0:1] op_sel_hi:[1,0,1]
	v_mul_f32_e32 v70, v53, v70
	v_mul_f32_e32 v20, v61, v74
	v_pk_fma_f32 v[6:7], v[10:11], v[52:53], v[6:7] op_sel_hi:[1,0,1]
	v_pk_fma_f32 v[4:5], v[8:9], v[52:53], v[4:5] op_sel_hi:[1,0,1]
	v_pk_fma_f32 v[2:3], v[10:11], v[16:17], v[2:3] op_sel_hi:[1,0,1]
	v_pk_fma_f32 v[0:1], v[8:9], v[16:17], v[0:1] op_sel_hi:[1,0,1]
	v_mul_f32_e32 v54, v54, v71
	v_mul_f32_e32 v22, v62, v75
	v_pk_fma_f32 v[6:7], v[34:35], v[70:71], v[6:7] op_sel_hi:[1,0,1]
	v_pk_fma_f32 v[4:5], v[32:33], v[70:71], v[4:5] op_sel_hi:[1,0,1]
	v_pk_fma_f32 v[2:3], v[34:35], v[20:21], v[2:3] op_sel_hi:[1,0,1]
	v_pk_fma_f32 v[0:1], v[32:33], v[20:21], v[0:1] op_sel_hi:[1,0,1]
	v_mul_f32_e32 v72, v55, v72
	v_mul_f32_e32 v44, v63, v76
	v_pk_fma_f32 v[6:7], v[38:39], v[54:55], v[6:7] op_sel_hi:[1,0,1]
	v_pk_fma_f32 v[4:5], v[36:37], v[54:55], v[4:5] op_sel_hi:[1,0,1]
	v_pk_fma_f32 v[2:3], v[38:39], v[22:23], v[2:3] op_sel_hi:[1,0,1]
	v_pk_fma_f32 v[0:1], v[36:37], v[22:23], v[0:1] op_sel_hi:[1,0,1]
	v_pk_fma_f32 v[6:7], v[42:43], v[72:73], v[6:7] op_sel_hi:[1,0,1]
	v_pk_fma_f32 v[4:5], v[40:41], v[72:73], v[4:5] op_sel_hi:[1,0,1]
	v_pk_fma_f32 v[2:3], v[42:43], v[44:45], v[2:3] op_sel_hi:[1,0,1]
	v_pk_fma_f32 v[0:1], v[40:41], v[44:45], v[0:1] op_sel_hi:[1,0,1]
	s_cmpk_eq_i32 s4, 0x200
	s_cbranch_scc1 .Lada2_last
; DI float silu(float x) { return x * __builtin_amdgcn_rcpf(1.f + __expf(-x)); }
; DI void p0_phase(const Params& P, LAS unsigned char* lds, int gw, int NGW, int wave, int lane) {
;     ...
;         for (int k = 0; k < 128; ++k) { const f32x4 w4 = *(const f32x4*)(wp + (size_t)k * NMOD);
;             const float c0 = silu(P.c[kc * 128 + k]), c1 = silu(P.c[D + kc * 128 + k]); a0 += w4 * c0; a1 += w4 * c1; }
	s_mov_b32 s0, 0xfffdc000
	v_add_co_u32_e64 v20, s[0:1], s0, v14
	s_add_u32 s8, s13, s4
	s_nop 0
	v_addc_co_u32_e64 v21, s[0:1], -1, v15, s[0:1]
	s_mov_b32 s0, 0xfffe8000
	s_nop 0
	v_add_co_u32_e64 v24, s[0:1], s0, v14
	v_add_co_u32_e32 v16, vcc, 0xfffd0000, v14
	s_nop 0
	v_addc_co_u32_e64 v25, s[0:1], -1, v15, s[0:1]
	s_mov_b32 s0, 0xffff4000
	s_nop 0
	v_add_co_u32_e64 v28, s[0:1], s0, v14
	s_addc_u32 s9, s14, s5
	s_nop 0
	v_addc_co_u32_e64 v29, s[0:1], -1, v15, s[0:1]
	v_add_co_u32_e64 v32, s[0:1], s31, v14
	global_load_dwordx4 v[8:11], v[14:15], off nt
	s_nop 0
	v_addc_co_u32_e64 v33, s[0:1], 0, v15, s[0:1]
	s_mov_b32 s0, 0x18000
	s_nop 0
	v_add_co_u32_e64 v36, s[0:1], s0, v14
	v_addc_co_u32_e32 v17, vcc, -1, v15, vcc
	s_nop 0
	v_addc_co_u32_e64 v37, s[0:1], 0, v15, s[0:1]
	s_mov_b32 s0, 0x24000
	s_nop 0
	v_add_co_u32_e64 v40, s[0:1], s0, v14
	s_nop 1
	v_addc_co_u32_e64 v41, s[0:1], 0, v15, s[0:1]
	s_mov_b64 s[0:1], 0x60000
	global_load_dwordx4 v[20:23], v[20:21], off nt
	s_nop 0
	global_load_dwordx4 v[24:27], v[24:25], off nt
	s_nop 0
	global_load_dwordx4 v[28:31], v[28:29], off nt
	s_nop 0
	global_load_dwordx4 v[32:35], v[32:33], off nt
	s_nop 0
	global_load_dwordx4 v[36:39], v[36:37], off nt
	s_nop 0
	global_load_dwordx4 v[40:43], v[40:41], off nt
	v_lshl_add_u64 v[14:15], v[14:15], 0, s[0:1]
	global_load_dwordx4 v[44:47], v97, s[8:9]
	global_load_dwordx4 v[48:51], v231, s[8:9]
	global_load_dwordx4 v[52:55], v97, s[8:9] offset:16
	global_load_dwordx4 v[56:59], v[16:17], off nt
	s_add_u32 s0, s8, 0x2000
	s_addc_u32 s1, s9, 0
	global_load_dwordx4 v[60:63], v97, s[0:1] offset:16
	s_add_u32 s4, s4, 32
	s_addc_u32 s5, s5, 0
	s_waitcnt vmcnt(12)
	v_mul_f32_e32 v16, 0xbfb8aa3b, v144
	v_mul_f32_e32 v17, 0xbfb8aa3b, v148
	v_mul_f32_e32 v19, 0xbfb8aa3b, v145
	v_mul_f32_e32 v64, 0xbfb8aa3b, v149
	v_exp_f32_e32 v16, v16
	v_exp_f32_e32 v17, v17
	v_mul_f32_e32 v65, 0xbfb8aa3b, v146
	v_mul_f32_e32 v66, 0xbfb8aa3b, v150
	v_exp_f32_e32 v19, v19
	v_exp_f32_e32 v64, v64
	v_mul_f32_e32 v67, 0xbfb8aa3b, v147
	v_mul_f32_e32 v68, 0xbfb8aa3b, v151
	v_exp_f32_e32 v65, v65
	v_exp_f32_e32 v66, v66
	v_mul_f32_e32 v69, 0xbfb8aa3b, v152
	v_exp_f32_e32 v67, v67
	v_exp_f32_e32 v68, v68
	v_mul_f32_e32 v73, 0xbfb8aa3b, v160
	v_mul_f32_e32 v70, 0xbfb8aa3b, v153
	v_exp_f32_e32 v69, v69
	v_mul_f32_e32 v74, 0xbfb8aa3b, v161
	v_exp_f32_e32 v73, v73
	v_add_f32_e32 v16, 1.0, v16
	v_add_f32_e32 v17, 1.0, v17
	v_mul_f32_e32 v71, 0xbfb8aa3b, v154
	v_exp_f32_e32 v70, v70
	v_mul_f32_e32 v75, 0xbfb8aa3b, v162
	v_exp_f32_e32 v74, v74
	v_add_f32_e32 v19, 1.0, v19
	v_add_f32_e32 v64, 1.0, v64
	v_rcp_f32_e32 v16, v16
	v_rcp_f32_e32 v17, v17
	v_mul_f32_e32 v72, 0xbfb8aa3b, v155
	v_exp_f32_e32 v71, v71
	v_mul_f32_e32 v76, 0xbfb8aa3b, v163
	v_exp_f32_e32 v75, v75
	v_add_f32_e32 v65, 1.0, v65
	v_add_f32_e32 v66, 1.0, v66
	v_rcp_f32_e32 v19, v19
	v_rcp_f32_e32 v64, v64
	v_exp_f32_e32 v72, v72
	v_exp_f32_e32 v76, v76
	v_add_f32_e32 v67, 1.0, v67
	v_add_f32_e32 v68, 1.0, v68
	v_rcp_f32_e32 v65, v65
	v_rcp_f32_e32 v66, v66
	v_add_f32_e32 v69, 1.0, v69
	v_rcp_f32_e32 v67, v67
	v_rcp_f32_e32 v68, v68
	v_add_f32_e32 v73, 1.0, v73
	v_add_f32_e32 v70, 1.0, v70
	v_rcp_f32_e32 v69, v69
	v_add_f32_e32 v74, 1.0, v74
	v_rcp_f32_e32 v73, v73
	v_mul_f32_e32 v16, v144, v16
	v_mul_f32_e32 v144, v148, v17
	v_add_f32_e32 v71, 1.0, v71
	v_rcp_f32_e32 v70, v70
	v_add_f32_e32 v75, 1.0, v75
	v_rcp_f32_e32 v74, v74
	v_mul_f32_e32 v148, v145, v19
	v_mul_f32_e32 v64, v149, v64
	v_pk_fma_f32 v[4:5], v[156:157], v[16:17], v[4:5] op_sel_hi:[1,0,1]
	v_pk_fma_f32 v[6:7], v[158:159], v[16:17], v[6:7] op_sel_hi:[1,0,1]
	v_pk_fma_f32 v[0:1], v[156:157], v[144:145], v[0:1] op_sel_hi:[1,0,1]
	v_pk_fma_f32 v[2:3], v[158:159], v[144:145], v[2:3] op_sel_hi:[1,0,1]
	v_add_f32_e32 v72, 1.0, v72
	v_rcp_f32_e32 v71, v71
	v_add_f32_e32 v76, 1.0, v76
	v_rcp_f32_e32 v75, v75
	v_mul_f32_e32 v146, v146, v65
	v_mul_f32_e32 v150, v150, v66
	v_pk_fma_f32 v[6:7], v[122:123], v[148:149], v[6:7] op_sel_hi:[1,0,1]
	v_pk_fma_f32 v[4:5], v[120:121], v[148:149], v[4:5] op_sel_hi:[1,0,1]
	v_pk_fma_f32 v[2:3], v[122:123], v[64:65], v[2:3] op_sel_hi:[1,0,1]
	v_pk_fma_f32 v[0:1], v[120:121], v[64:65], v[0:1] op_sel_hi:[1,0,1]
	v_rcp_f32_e32 v72, v72
	v_rcp_f32_e32 v76, v76
	v_mul_f32_e32 v66, v147, v67
	v_mul_f32_e32 v68, v151, v68
	v_pk_fma_f32 v[6:7], v[126:127], v[146:147], v[6:7] op_sel_hi:[1,0,1]
	v_pk_fma_f32 v[4:5], v[124:125], v[146:147], v[4:5] op_sel_hi:[1,0,1]
	v_pk_fma_f32 v[2:3], v[126:127], v[150:151], v[2:3] op_sel_hi:[1,0,1]
	v_pk_fma_f32 v[0:1], v[124:125], v[150:151], v[0:1] op_sel_hi:[1,0,1]
	v_mul_f32_e32 v152, v152, v69
	v_mul_f32_e32 v16, v160, v73
	v_pk_fma_f32 v[6:7], v[130:131], v[66:67], v[6:7] op_sel_hi:[1,0,1]
	v_pk_fma_f32 v[4:5], v[128:129], v[66:67], v[4:5] op_sel_hi:[1,0,1]
	v_pk_fma_f32 v[2:3], v[130:131], v[68:69], v[2:3] op_sel_hi:[1,0,1]
	v_pk_fma_f32 v[0:1], v[128:129], v[68:69], v[0:1] op_sel_hi:[1,0,1]
	v_mul_f32_e32 v70, v153, v70
	v_mul_f32_e32 v120, v161, v74
	v_pk_fma_f32 v[6:7], v[110:111], v[152:153], v[6:7] op_sel_hi:[1,0,1]
	v_pk_fma_f32 v[4:5], v[108:109], v[152:153], v[4:5] op_sel_hi:[1,0,1]
	v_pk_fma_f32 v[2:3], v[110:111], v[16:17], v[2:3] op_sel_hi:[1,0,1]
	v_pk_fma_f32 v[0:1], v[108:109], v[16:17], v[0:1] op_sel_hi:[1,0,1]
	v_mul_f32_e32 v154, v154, v71
	v_mul_f32_e32 v122, v162, v75
	v_pk_fma_f32 v[6:7], v[134:135], v[70:71], v[6:7] op_sel_hi:[1,0,1]
	v_pk_fma_f32 v[4:5], v[132:133], v[70:71], v[4:5] op_sel_hi:[1,0,1]
	v_pk_fma_f32 v[2:3], v[134:135], v[120:121], v[2:3] op_sel_hi:[1,0,1]
	v_pk_fma_f32 v[0:1], v[132:133], v[120:121], v[0:1] op_sel_hi:[1,0,1]
	v_mul_f32_e32 v72, v155, v72
	v_mul_f32_e32 v144, v163, v76
	v_pk_fma_f32 v[6:7], v[138:139], v[154:155], v[6:7] op_sel_hi:[1,0,1]
	v_pk_fma_f32 v[4:5], v[136:137], v[154:155], v[4:5] op_sel_hi:[1,0,1]
	v_pk_fma_f32 v[2:3], v[138:139], v[122:123], v[2:3] op_sel_hi:[1,0,1]
	v_pk_fma_f32 v[0:1], v[136:137], v[122:123], v[0:1] op_sel_hi:[1,0,1]
	v_pk_fma_f32 v[6:7], v[142:143], v[72:73], v[6:7] op_sel_hi:[1,0,1]
	v_pk_fma_f32 v[4:5], v[140:141], v[72:73], v[4:5] op_sel_hi:[1,0,1]
	v_pk_fma_f32 v[2:3], v[142:143], v[144:145], v[2:3] op_sel_hi:[1,0,1]
	v_pk_fma_f32 v[0:1], v[140:141], v[144:145], v[0:1] op_sel_hi:[1,0,1]
	s_branch .Lada2_pair
